# P2 item loop as well: static s_setprio 1 for waves 4-7, reset at the loop exit
# baseline (speedup 1.0000x reference)
.LBB0_265:
	s_cmp_lt_i32 s79, 3
	s_cselect_b64 s[0:1], -1, 0
	s_and_b64 s[0:1], s[0:1], s[4:5]
	s_andn2_b64 vcc, exec, s[0:1]
	s_cbranch_vccnz .LBB0_279
	s_mov_b64 s[4:5], s[92:93]
	s_and_b32 s59, s58, 0xffffffc0
	s_waitcnt vmcnt(0)
	v_mbcnt_lo_u32_b32 v2, -1, 0
	v_mbcnt_hi_u32_b32 v2, -1, v2
	s_cmpk_gt_i32 s2, 0xff
	v_add_u32_e32 v62, s59, v2
	s_cbranch_scc1 .LBB0_279
	s_load_dwordx4 s[12:15], s[4:5], 0x68
	s_load_dwordx4 s[16:19], s[4:5], 0x18
	v_and_b32_e32 v84, 0x7f, v62
	v_lshl_add_u32 v85, v84, 2, 0
	v_ashrrev_i32_e32 v88, 4, v62
	s_waitcnt lgkmcnt(0)
	s_add_u32 s26, s14, 0x4000000
	s_addc_u32 s27, s15, 0
	s_add_u32 s10, s14, 0xf00000
	s_addc_u32 s11, s15, 0
	s_add_u32 s20, s14, 0xb000000
	s_addc_u32 s21, s15, 0
	s_lshr_b32 s0, s58, 7
	s_lshl_b32 s4, s0, 12
	s_add_i32 s28, s4, 0
	s_and_b32 s4, s58, 0x3fffff80
	s_lshl_b32 s29, s0, 14
	s_add_i32 s30, 0, 0x10800
	s_cmpk_lg_i32 s52, 0x100
	s_cselect_b64 s[22:23], -1, 0
	s_lshl_b32 s0, s0, 3
	s_cmpk_lt_u32 s58, 0x80
	s_cselect_b64 s[24:25], -1, 0
	s_ashr_i32 s60, s59, 31
	v_lshl_add_u32 v87, s4, 2, v85
	s_movk_i32 s4, 0x1fc
	s_cmpk_gt_u32 s58, 0xff
	v_xor_b32_e32 v4, v88, v62
	v_mad_u32_u24 v8, v84, s4, v85
	s_cselect_b64 s[4:5], -1, 0
	s_cmpk_gt_u32 s58, 0x17f
	v_lshlrev_b32_e32 v4, 4, v4
	s_cselect_b64 s[6:7], -1, 0
	s_cmpk_gt_u32 s58, 0x1ff
	v_lshl_add_u32 v3, v88, 8, s30
	v_and_b32_e32 v6, 0xf0, v4
	v_lshlrev_b32_e32 v4, 1, v62
	s_cselect_b64 s[8:9], -1, 0
	s_add_i32 s30, s30, s29
	s_movk_i32 s29, 0x50
	v_mov_b32_e32 v14, 0xf0
	v_bitop3_b32 v15, v4, s29, v14 bitop3:0x6c
	s_movk_i32 s29, 0x60
	v_bitop3_b32 v16, v4, s29, v14 bitop3:0x6c
	s_movk_i32 s29, 0x70
	v_bitop3_b32 v17, v4, s29, v14 bitop3:0x6c
	s_movk_i32 s29, 0x90
	v_bitop3_b32 v20, v4, s29, v14 bitop3:0x6c
	s_movk_i32 s29, 0xa0
	v_bitop3_b32 v21, v4, s29, v14 bitop3:0x6c
	s_movk_i32 s29, 0xb0
	v_bitop3_b32 v22, v4, s29, v14 bitop3:0x6c
	s_movk_i32 s29, 0xc0
	v_bitop3_b32 v23, v4, s29, v14 bitop3:0x6c
	s_movk_i32 s29, 0xd0
	s_movk_i32 s31, 0xf0
	s_movk_i32 s34, 0x80
	v_bitop3_b32 v24, v4, s29, v14 bitop3:0x6c
	s_movk_i32 s29, 0xe0
	v_and_b32_e32 v7, 14, v4
	v_and_b32_e32 v5, 15, v62
	v_and_b32_e32 v9, 0xf0, v4
	v_bitop3_b32 v19, v4, s34, v14 bitop3:0x6c
	v_bitop3_b32 v14, v4, s29, v14 bitop3:0x6c
	v_bitop3_b32 v4, v4, s31, v4 bitop3:0xc
	v_add_u32_e32 v25, s30, v4
	v_bitop3_b32 v4, s0, v5, 1 bitop3:0x36
	v_lshlrev_b32_e32 v26, 4, v4
	v_bitop3_b32 v4, s0, v5, 2 bitop3:0x36
	v_lshlrev_b32_e32 v27, 4, v4
	v_bitop3_b32 v4, s0, v5, 3 bitop3:0x36
	v_lshlrev_b32_e32 v28, 4, v4
	v_bitop3_b32 v4, s0, v5, 4 bitop3:0x36
	v_lshlrev_b32_e32 v29, 4, v4
	v_bitop3_b32 v4, s0, v5, 5 bitop3:0x36
	v_lshlrev_b32_e32 v30, 4, v4
	v_bitop3_b32 v4, s0, v5, 6 bitop3:0x36
	v_ashrrev_i32_e32 v63, 31, v62
	v_lshlrev_b32_e32 v2, 3, v62
	v_bitop3_b32 v18, s0, v62, 15 bitop3:0x78
	v_lshlrev_b32_e32 v31, 4, v4
	v_bitop3_b32 v4, s0, v5, 7 bitop3:0x36
	v_and_b32_e32 v2, 0x78, v2
	v_mov_b32_e32 v65, 0
	v_add_u32_e32 v10, s30, v9
	v_xad_u32 v11, v9, 16, s30
	v_xad_u32 v12, v9, 32, s30
	v_xad_u32 v13, v9, 48, s30
	v_xad_u32 v9, v9, 64, s30
	v_add_u32_e32 v15, s30, v15
	v_add_u32_e32 v16, s30, v16
	v_add_u32_e32 v17, s30, v17
	v_lshlrev_b32_e32 v18, 4, v18
	v_add_u32_e32 v19, s30, v19
	v_add_u32_e32 v20, s30, v20
	v_add_u32_e32 v21, s30, v21
	v_add_u32_e32 v22, s30, v22
	v_add_u32_e32 v23, s30, v23
	v_add_u32_e32 v24, s30, v24
	v_add_u32_e32 v14, s30, v14
	v_lshlrev_b32_e32 v32, 4, v4
	v_lshl_add_u64 v[4:5], v[62:63], 4, s[14:15]
	s_mov_b64 s[14:15], 0xe00000
	s_mov_b32 s1, 0
	v_lshl_add_u32 v86, v62, 4, 0
	v_lshl_add_u64 v[66:67], v[4:5], 0, s[14:15]
	s_movk_i32 s61, 0x2000
	s_movk_i32 s62, 0x1000
	s_movk_i32 s63, 0x3000
	v_mov_b32_e32 v63, s28
	s_mov_b32 s64, 0xbfb8aa3b
	s_mov_b32 s65, 0x3d800000
	s_movk_i32 s66, 0x1800
	v_mov_b64_e32 v[68:69], s[26:27]
	v_lshlrev_b32_e32 v70, 1, v2
	v_mov_b32_e32 v71, v65
	s_mov_b64 s[14:15], 0x30000
	s_mov_b64 s[26:27], 0x60000
	s_mov_b32 s67, 0x60000
	s_mov_b64 s[28:29], 0x90000
	s_mov_b64 s[30:31], 0xc0000
	s_mov_b32 s68, 0xc0000
	s_mov_b64 s[34:35], 0xf0000
	s_mov_b64 s[36:37], 0x120000
	s_mov_b64 s[38:39], 0x150000
	v_add_u32_e32 v89, v8, v18
	v_add_u32_e32 v90, v8, v26
	v_add_u32_e32 v91, v8, v27
	v_add_u32_e32 v92, v8, v28
	v_add_u32_e32 v93, v8, v29
	v_add_u32_e32 v94, v8, v30
	v_add_u32_e32 v95, v8, v31
	v_add_u32_e32 v96, v8, v32
	s_mov_b32 s69, 0x20000
	s_mov_b32 s70, 0x40000
	s_mov_b32 s71, 0x80000
	s_mov_b32 s72, 0xa0000
	s_mov_b32 s73, 0xe0000
	v_add_u32_e32 v97, v3, v6
	v_add_u32_e32 v98, v10, v7
	v_add_u32_e32 v99, v11, v7
	v_add_u32_e32 v100, v12, v7
	v_add_u32_e32 v101, v13, v7
	v_add_u32_e32 v102, v9, v7
	v_add_u32_e32 v103, v15, v7
	v_add_u32_e32 v104, v16, v7
	v_add_u32_e32 v105, v17, v7
	v_add_u32_e32 v106, v19, v7
	v_add_u32_e32 v107, v20, v7
	v_add_u32_e32 v108, v21, v7
	v_add_u32_e32 v109, v22, v7
	v_add_u32_e32 v110, v23, v7
	v_add_u32_e32 v111, v24, v7
	v_add_u32_e32 v112, v14, v7
	v_add_u32_e32 v113, v25, v7
	s_mov_b32 s44, s2
	s_cmp_lt_u32 s54, 4
	s_cbranch_scc1 .Lp2prio_skip
	s_setprio 1
.Lp2prio_skip:
	s_branch .LBB0_269
.LBB0_268:
	s_lshl_b32 s46, s46, 3
	s_ashr_i32 s47, s46, 31
	s_lshl_b64 s[46:47], s[46:47], 11
	s_lshl_b32 s0, s45, 9
	s_add_u32 s0, s0, s59
	s_addc_u32 s45, 0, s60
	v_mov_b32_e32 v234, v62
	s_add_u32 s0, s0, s46
	s_addc_u32 s45, s45, s47
	v_and_b32_e32 v235, 15, v234
	v_or_b32_e32 v2, s0, v235
	v_mov_b32_e32 v3, s45
	v_bfe_u32 v214, v234, 4, 2
	v_lshlrev_b64 v[2:3], 6, v[2:3]
	v_lshrrev_b32_e32 v12, 4, v234
	v_lshl_add_u64 v[2:3], s[12:13], 0, v[2:3]
	v_lshlrev_b32_e32 v64, 4, v214
	v_bitop3_b32 v12, v12, v235, 3 bitop3:0x6c
	v_lshl_add_u64 v[2:3], v[2:3], 0, v[64:65]
	v_lshlrev_b32_e32 v64, 9, v235
	v_lshlrev_b32_e32 v12, 4, v12
	v_add3_u32 v60, 0, v12, v64
	ds_read_b128 v[12:15], v60
	ds_read_b128 v[16:19], v60 offset:8192
	ds_read_b128 v[52:55], v60 offset:16384
	ds_read_b128 v[56:59], v60 offset:24576
	ds_read_b128 v[126:129], v60 offset:32768
	ds_read_b128 v[130:133], v60 offset:40960
	ds_read_b128 v[158:161], v60 offset:49152
	ds_read_b128 v[162:165], v60 offset:57344
	v_add_co_u32_e32 v60, vcc, s69, v2
	s_waitcnt lgkmcnt(7)
	v_mfma_f32_16x16x32_bf16 v[20:23], v[12:15], v[236:239], 0
	v_addc_co_u32_e32 v61, vcc, 0, v3, vcc
	global_load_dwordx4 v[178:181], v[60:61], off
	global_load_dwordx4 v[182:185], v[60:61], off offset:1024
	global_load_dwordx4 v[186:189], v[60:61], off offset:2048
	global_load_dwordx4 v[190:193], v[60:61], off offset:3072
	s_waitcnt vmcnt(6)
	v_mfma_f32_16x16x32_bf16 v[28:31], v[12:15], v[240:243], 0
	s_waitcnt vmcnt(5)
	v_mfma_f32_16x16x32_bf16 v[36:39], v[12:15], v[244:247], 0
	s_waitcnt vmcnt(4)
	v_mfma_f32_16x16x32_bf16 v[12:15], v[12:15], v[248:251], 0
	s_waitcnt lgkmcnt(6)
	v_mfma_f32_16x16x32_bf16 v[40:43], v[16:19], v[236:239], 0
	v_mfma_f32_16x16x32_bf16 v[44:47], v[16:19], v[240:243], 0
	v_mfma_f32_16x16x32_bf16 v[48:51], v[16:19], v[244:247], 0
	v_mfma_f32_16x16x32_bf16 v[16:19], v[16:19], v[248:251], 0
	s_waitcnt lgkmcnt(5)
	v_mfma_f32_16x16x32_bf16 v[72:75], v[52:55], v[236:239], 0
	v_mfma_f32_16x16x32_bf16 v[76:79], v[52:55], v[240:243], 0
	v_mfma_f32_16x16x32_bf16 v[80:83], v[52:55], v[244:247], 0
	v_mfma_f32_16x16x32_bf16 v[52:55], v[52:55], v[248:251], 0
	s_waitcnt lgkmcnt(4)
	v_mfma_f32_16x16x32_bf16 v[114:117], v[56:59], v[236:239], 0
	v_mfma_f32_16x16x32_bf16 v[118:121], v[56:59], v[240:243], 0
	v_mfma_f32_16x16x32_bf16 v[122:125], v[56:59], v[244:247], 0
	v_mfma_f32_16x16x32_bf16 v[56:59], v[56:59], v[248:251], 0
	s_waitcnt lgkmcnt(3)
	v_mfma_f32_16x16x32_bf16 v[134:137], v[126:129], v[236:239], 0
	v_mfma_f32_16x16x32_bf16 v[138:141], v[126:129], v[240:243], 0
	v_mfma_f32_16x16x32_bf16 v[142:145], v[126:129], v[244:247], 0
	v_mfma_f32_16x16x32_bf16 v[126:129], v[126:129], v[248:251], 0
	s_waitcnt lgkmcnt(2)
	v_mfma_f32_16x16x32_bf16 v[146:149], v[130:133], v[236:239], 0
	v_mfma_f32_16x16x32_bf16 v[150:153], v[130:133], v[240:243], 0
	v_mfma_f32_16x16x32_bf16 v[154:157], v[130:133], v[244:247], 0
	v_mfma_f32_16x16x32_bf16 v[130:133], v[130:133], v[248:251], 0
	s_waitcnt lgkmcnt(1)
	v_mfma_f32_16x16x32_bf16 v[166:169], v[158:161], v[236:239], 0
	v_mfma_f32_16x16x32_bf16 v[170:173], v[158:161], v[240:243], 0
	v_mfma_f32_16x16x32_bf16 v[174:177], v[158:161], v[244:247], 0
	v_mfma_f32_16x16x32_bf16 v[158:161], v[158:161], v[248:251], 0
	s_waitcnt lgkmcnt(0)
	v_mfma_f32_16x16x32_bf16 v[4:7], v[162:165], v[236:239], 0
	v_mfma_f32_16x16x32_bf16 v[8:11], v[162:165], v[240:243], 0
	v_mfma_f32_16x16x32_bf16 v[24:27], v[162:165], v[244:247], 0
	v_mfma_f32_16x16x32_bf16 v[32:35], v[162:165], v[248:251], 0
	v_add_co_u32_e32 v60, vcc, s70, v2
	s_nop 1
	v_addc_co_u32_e32 v61, vcc, 0, v3, vcc
	global_load_dwordx4 v[162:165], v[60:61], off
	global_load_dwordx4 v[194:197], v[60:61], off offset:1024
	global_load_dwordx4 v[198:201], v[60:61], off offset:2048
	global_load_dwordx4 v[202:205], v[60:61], off offset:3072
	v_bitop3_b32 v60, v214, v235, 4 bitop3:0x36
	v_lshlrev_b32_e32 v60, 4, v60
	v_add3_u32 v60, 0, v60, v64
	ds_read_b128 v[206:209], v60
	ds_read_b128 v[210:213], v60 offset:8192
	s_waitcnt vmcnt(7) lgkmcnt(1)
	v_mfma_f32_16x16x32_bf16 v[20:23], v[206:209], v[178:181], v[20:23]
	s_waitcnt vmcnt(6)
	v_mfma_f32_16x16x32_bf16 v[28:31], v[206:209], v[182:185], v[28:31]
	s_waitcnt vmcnt(5)
	v_mfma_f32_16x16x32_bf16 v[36:39], v[206:209], v[186:189], v[36:39]
	s_waitcnt vmcnt(4)
	v_mfma_f32_16x16x32_bf16 v[12:15], v[206:209], v[190:193], v[12:15]
	s_waitcnt lgkmcnt(0)
	v_mfma_f32_16x16x32_bf16 v[40:43], v[210:213], v[178:181], v[40:43]
	v_mfma_f32_16x16x32_bf16 v[44:47], v[210:213], v[182:185], v[44:47]
	v_mfma_f32_16x16x32_bf16 v[48:51], v[210:213], v[186:189], v[48:51]
	v_mfma_f32_16x16x32_bf16 v[16:19], v[210:213], v[190:193], v[16:19]
	ds_read_b128 v[206:209], v60 offset:16384
	ds_read_b128 v[210:213], v60 offset:24576
	s_waitcnt lgkmcnt(1)
	v_mfma_f32_16x16x32_bf16 v[72:75], v[206:209], v[178:181], v[72:75]
	v_mfma_f32_16x16x32_bf16 v[76:79], v[206:209], v[182:185], v[76:79]
	v_mfma_f32_16x16x32_bf16 v[80:83], v[206:209], v[186:189], v[80:83]
	v_mfma_f32_16x16x32_bf16 v[52:55], v[206:209], v[190:193], v[52:55]
	s_waitcnt lgkmcnt(0)
	v_mfma_f32_16x16x32_bf16 v[114:117], v[210:213], v[178:181], v[114:117]
	v_mfma_f32_16x16x32_bf16 v[118:121], v[210:213], v[182:185], v[118:121]
	v_mfma_f32_16x16x32_bf16 v[122:125], v[210:213], v[186:189], v[122:125]
	v_mfma_f32_16x16x32_bf16 v[56:59], v[210:213], v[190:193], v[56:59]
	ds_read_b128 v[206:209], v60 offset:32768
	ds_read_b128 v[210:213], v60 offset:40960
	s_waitcnt lgkmcnt(1)
	v_mfma_f32_16x16x32_bf16 v[134:137], v[206:209], v[178:181], v[134:137]
	v_mfma_f32_16x16x32_bf16 v[138:141], v[206:209], v[182:185], v[138:141]
	v_mfma_f32_16x16x32_bf16 v[142:145], v[206:209], v[186:189], v[142:145]
	v_mfma_f32_16x16x32_bf16 v[126:129], v[206:209], v[190:193], v[126:129]
	s_waitcnt lgkmcnt(0)
	v_mfma_f32_16x16x32_bf16 v[146:149], v[210:213], v[178:181], v[146:149]
	v_mfma_f32_16x16x32_bf16 v[150:153], v[210:213], v[182:185], v[150:153]
	v_mfma_f32_16x16x32_bf16 v[154:157], v[210:213], v[186:189], v[154:157]
	v_mfma_f32_16x16x32_bf16 v[130:133], v[210:213], v[190:193], v[130:133]
	ds_read_b128 v[206:209], v60 offset:49152
	ds_read_b128 v[210:213], v60 offset:57344
	s_waitcnt lgkmcnt(1)
	v_mfma_f32_16x16x32_bf16 v[166:169], v[206:209], v[178:181], v[166:169]
	v_mfma_f32_16x16x32_bf16 v[170:173], v[206:209], v[182:185], v[170:173]
	v_mfma_f32_16x16x32_bf16 v[174:177], v[206:209], v[186:189], v[174:177]
	v_mfma_f32_16x16x32_bf16 v[158:161], v[206:209], v[190:193], v[158:161]
	s_waitcnt lgkmcnt(0)
	v_mfma_f32_16x16x32_bf16 v[4:7], v[210:213], v[178:181], v[4:7]
	v_mfma_f32_16x16x32_bf16 v[8:11], v[210:213], v[182:185], v[8:11]
	v_mfma_f32_16x16x32_bf16 v[24:27], v[210:213], v[186:189], v[24:27]
	v_mfma_f32_16x16x32_bf16 v[32:35], v[210:213], v[190:193], v[32:35]
	v_add_co_u32_e32 v60, vcc, s67, v2
	s_nop 1
	v_addc_co_u32_e32 v61, vcc, 0, v3, vcc
	global_load_dwordx4 v[178:181], v[60:61], off
	global_load_dwordx4 v[182:185], v[60:61], off offset:1024
	global_load_dwordx4 v[186:189], v[60:61], off offset:2048
	global_load_dwordx4 v[190:193], v[60:61], off offset:3072
	v_bitop3_b32 v60, v214, v235, 8 bitop3:0x36
	v_lshlrev_b32_e32 v60, 4, v60
	v_add3_u32 v60, 0, v60, v64
	ds_read_b128 v[206:209], v60
	ds_read_b128 v[210:213], v60 offset:8192
	s_waitcnt vmcnt(7) lgkmcnt(1)
	v_mfma_f32_16x16x32_bf16 v[20:23], v[206:209], v[162:165], v[20:23]
	s_waitcnt vmcnt(6)
	v_mfma_f32_16x16x32_bf16 v[28:31], v[206:209], v[194:197], v[28:31]
	s_waitcnt vmcnt(5)
	v_mfma_f32_16x16x32_bf16 v[36:39], v[206:209], v[198:201], v[36:39]
	s_waitcnt vmcnt(4)
	v_mfma_f32_16x16x32_bf16 v[12:15], v[206:209], v[202:205], v[12:15]
	s_waitcnt lgkmcnt(0)
	v_mfma_f32_16x16x32_bf16 v[40:43], v[210:213], v[162:165], v[40:43]
	v_mfma_f32_16x16x32_bf16 v[44:47], v[210:213], v[194:197], v[44:47]
	v_mfma_f32_16x16x32_bf16 v[48:51], v[210:213], v[198:201], v[48:51]
	v_mfma_f32_16x16x32_bf16 v[16:19], v[210:213], v[202:205], v[16:19]
	ds_read_b128 v[206:209], v60 offset:16384
	ds_read_b128 v[210:213], v60 offset:24576
	s_waitcnt lgkmcnt(1)
	v_mfma_f32_16x16x32_bf16 v[72:75], v[206:209], v[162:165], v[72:75]
	v_mfma_f32_16x16x32_bf16 v[76:79], v[206:209], v[194:197], v[76:79]
	v_mfma_f32_16x16x32_bf16 v[80:83], v[206:209], v[198:201], v[80:83]
	v_mfma_f32_16x16x32_bf16 v[52:55], v[206:209], v[202:205], v[52:55]
	s_waitcnt lgkmcnt(0)
	v_mfma_f32_16x16x32_bf16 v[114:117], v[210:213], v[162:165], v[114:117]
	v_mfma_f32_16x16x32_bf16 v[118:121], v[210:213], v[194:197], v[118:121]
	v_mfma_f32_16x16x32_bf16 v[122:125], v[210:213], v[198:201], v[122:125]
	v_mfma_f32_16x16x32_bf16 v[56:59], v[210:213], v[202:205], v[56:59]
	ds_read_b128 v[206:209], v60 offset:32768
	ds_read_b128 v[210:213], v60 offset:40960
	s_waitcnt lgkmcnt(1)
	v_mfma_f32_16x16x32_bf16 v[134:137], v[206:209], v[162:165], v[134:137]
	v_mfma_f32_16x16x32_bf16 v[138:141], v[206:209], v[194:197], v[138:141]
	v_mfma_f32_16x16x32_bf16 v[142:145], v[206:209], v[198:201], v[142:145]
	v_mfma_f32_16x16x32_bf16 v[126:129], v[206:209], v[202:205], v[126:129]
	s_waitcnt lgkmcnt(0)
	v_mfma_f32_16x16x32_bf16 v[146:149], v[210:213], v[162:165], v[146:149]
	v_mfma_f32_16x16x32_bf16 v[150:153], v[210:213], v[194:197], v[150:153]
	v_mfma_f32_16x16x32_bf16 v[154:157], v[210:213], v[198:201], v[154:157]
	v_mfma_f32_16x16x32_bf16 v[130:133], v[210:213], v[202:205], v[130:133]
	ds_read_b128 v[206:209], v60 offset:49152
	ds_read_b128 v[210:213], v60 offset:57344
	s_waitcnt lgkmcnt(1)
	v_mfma_f32_16x16x32_bf16 v[166:169], v[206:209], v[162:165], v[166:169]
	v_mfma_f32_16x16x32_bf16 v[170:173], v[206:209], v[194:197], v[170:173]
	v_mfma_f32_16x16x32_bf16 v[174:177], v[206:209], v[198:201], v[174:177]
	v_mfma_f32_16x16x32_bf16 v[158:161], v[206:209], v[202:205], v[158:161]
	s_waitcnt lgkmcnt(0)
	v_mfma_f32_16x16x32_bf16 v[4:7], v[210:213], v[162:165], v[4:7]
	v_mfma_f32_16x16x32_bf16 v[8:11], v[210:213], v[194:197], v[8:11]
	v_mfma_f32_16x16x32_bf16 v[24:27], v[210:213], v[198:201], v[24:27]
	v_mfma_f32_16x16x32_bf16 v[32:35], v[210:213], v[202:205], v[32:35]
	v_add_co_u32_e32 v60, vcc, s71, v2
	s_nop 1
	v_addc_co_u32_e32 v61, vcc, 0, v3, vcc
	global_load_dwordx4 v[162:165], v[60:61], off
	global_load_dwordx4 v[194:197], v[60:61], off offset:1024
	global_load_dwordx4 v[198:201], v[60:61], off offset:2048
	global_load_dwordx4 v[202:205], v[60:61], off offset:3072
	v_bitop3_b32 v60, v214, v235, 12 bitop3:0x36
	v_lshlrev_b32_e32 v60, 4, v60
	v_add3_u32 v60, 0, v60, v64
	ds_read_b128 v[206:209], v60
	ds_read_b128 v[210:213], v60 offset:8192
	s_waitcnt vmcnt(7) lgkmcnt(1)
	v_mfma_f32_16x16x32_bf16 v[20:23], v[206:209], v[178:181], v[20:23]
	s_waitcnt vmcnt(6)
	v_mfma_f32_16x16x32_bf16 v[28:31], v[206:209], v[182:185], v[28:31]
	s_waitcnt vmcnt(5)
	v_mfma_f32_16x16x32_bf16 v[36:39], v[206:209], v[186:189], v[36:39]
	s_waitcnt vmcnt(4)
	v_mfma_f32_16x16x32_bf16 v[12:15], v[206:209], v[190:193], v[12:15]
	s_waitcnt lgkmcnt(0)
	v_mfma_f32_16x16x32_bf16 v[40:43], v[210:213], v[178:181], v[40:43]
	v_mfma_f32_16x16x32_bf16 v[44:47], v[210:213], v[182:185], v[44:47]
	v_mfma_f32_16x16x32_bf16 v[48:51], v[210:213], v[186:189], v[48:51]
	v_mfma_f32_16x16x32_bf16 v[16:19], v[210:213], v[190:193], v[16:19]
	ds_read_b128 v[206:209], v60 offset:16384
	ds_read_b128 v[210:213], v60 offset:24576
	s_waitcnt lgkmcnt(1)
	v_mfma_f32_16x16x32_bf16 v[72:75], v[206:209], v[178:181], v[72:75]
	v_mfma_f32_16x16x32_bf16 v[76:79], v[206:209], v[182:185], v[76:79]
	v_mfma_f32_16x16x32_bf16 v[80:83], v[206:209], v[186:189], v[80:83]
	v_mfma_f32_16x16x32_bf16 v[52:55], v[206:209], v[190:193], v[52:55]
	s_waitcnt lgkmcnt(0)
	v_mfma_f32_16x16x32_bf16 v[114:117], v[210:213], v[178:181], v[114:117]
	v_mfma_f32_16x16x32_bf16 v[118:121], v[210:213], v[182:185], v[118:121]
	v_mfma_f32_16x16x32_bf16 v[122:125], v[210:213], v[186:189], v[122:125]
	v_mfma_f32_16x16x32_bf16 v[56:59], v[210:213], v[190:193], v[56:59]
	ds_read_b128 v[206:209], v60 offset:32768
	ds_read_b128 v[210:213], v60 offset:40960
	s_waitcnt lgkmcnt(1)
	v_mfma_f32_16x16x32_bf16 v[134:137], v[206:209], v[178:181], v[134:137]
	v_mfma_f32_16x16x32_bf16 v[138:141], v[206:209], v[182:185], v[138:141]
	v_mfma_f32_16x16x32_bf16 v[142:145], v[206:209], v[186:189], v[142:145]
	v_mfma_f32_16x16x32_bf16 v[126:129], v[206:209], v[190:193], v[126:129]
	s_waitcnt lgkmcnt(0)
	v_mfma_f32_16x16x32_bf16 v[146:149], v[210:213], v[178:181], v[146:149]
	v_mfma_f32_16x16x32_bf16 v[150:153], v[210:213], v[182:185], v[150:153]
	v_mfma_f32_16x16x32_bf16 v[154:157], v[210:213], v[186:189], v[154:157]
	v_mfma_f32_16x16x32_bf16 v[130:133], v[210:213], v[190:193], v[130:133]
	ds_read_b128 v[206:209], v60 offset:49152
	ds_read_b128 v[210:213], v60 offset:57344
	s_waitcnt lgkmcnt(1)
	v_mfma_f32_16x16x32_bf16 v[166:169], v[206:209], v[178:181], v[166:169]
	v_mfma_f32_16x16x32_bf16 v[170:173], v[206:209], v[182:185], v[170:173]
	v_mfma_f32_16x16x32_bf16 v[174:177], v[206:209], v[186:189], v[174:177]
	v_mfma_f32_16x16x32_bf16 v[158:161], v[206:209], v[190:193], v[158:161]
	s_waitcnt lgkmcnt(0)
	v_mfma_f32_16x16x32_bf16 v[4:7], v[210:213], v[178:181], v[4:7]
	v_mfma_f32_16x16x32_bf16 v[8:11], v[210:213], v[182:185], v[8:11]
	v_mfma_f32_16x16x32_bf16 v[24:27], v[210:213], v[186:189], v[24:27]
	v_mfma_f32_16x16x32_bf16 v[32:35], v[210:213], v[190:193], v[32:35]
	v_add_co_u32_e32 v60, vcc, s72, v2
	s_nop 1
	v_addc_co_u32_e32 v61, vcc, 0, v3, vcc
	global_load_dwordx4 v[178:181], v[60:61], off
	global_load_dwordx4 v[182:185], v[60:61], off offset:1024
	global_load_dwordx4 v[186:189], v[60:61], off offset:2048
	global_load_dwordx4 v[190:193], v[60:61], off offset:3072
	v_bitop3_b32 v60, v214, v235, 16 bitop3:0x36
	v_lshlrev_b32_e32 v60, 4, v60
	v_add3_u32 v60, 0, v60, v64
	ds_read_b128 v[206:209], v60
	ds_read_b128 v[210:213], v60 offset:8192
	s_waitcnt vmcnt(7) lgkmcnt(1)
	v_mfma_f32_16x16x32_bf16 v[20:23], v[206:209], v[162:165], v[20:23]
	s_waitcnt vmcnt(6)
	v_mfma_f32_16x16x32_bf16 v[28:31], v[206:209], v[194:197], v[28:31]
	s_waitcnt vmcnt(5)
	v_mfma_f32_16x16x32_bf16 v[36:39], v[206:209], v[198:201], v[36:39]
	s_waitcnt vmcnt(4)
	v_mfma_f32_16x16x32_bf16 v[12:15], v[206:209], v[202:205], v[12:15]
	s_waitcnt lgkmcnt(0)
	v_mfma_f32_16x16x32_bf16 v[40:43], v[210:213], v[162:165], v[40:43]
	v_mfma_f32_16x16x32_bf16 v[44:47], v[210:213], v[194:197], v[44:47]
	v_mfma_f32_16x16x32_bf16 v[48:51], v[210:213], v[198:201], v[48:51]
	v_mfma_f32_16x16x32_bf16 v[16:19], v[210:213], v[202:205], v[16:19]
	ds_read_b128 v[206:209], v60 offset:16384
	ds_read_b128 v[210:213], v60 offset:24576
	s_waitcnt lgkmcnt(1)
	v_mfma_f32_16x16x32_bf16 v[72:75], v[206:209], v[162:165], v[72:75]
	v_mfma_f32_16x16x32_bf16 v[76:79], v[206:209], v[194:197], v[76:79]
	v_mfma_f32_16x16x32_bf16 v[80:83], v[206:209], v[198:201], v[80:83]
	v_mfma_f32_16x16x32_bf16 v[52:55], v[206:209], v[202:205], v[52:55]
	s_waitcnt lgkmcnt(0)
	v_mfma_f32_16x16x32_bf16 v[114:117], v[210:213], v[162:165], v[114:117]
	v_mfma_f32_16x16x32_bf16 v[118:121], v[210:213], v[194:197], v[118:121]
	v_mfma_f32_16x16x32_bf16 v[122:125], v[210:213], v[198:201], v[122:125]
	v_mfma_f32_16x16x32_bf16 v[56:59], v[210:213], v[202:205], v[56:59]
	ds_read_b128 v[206:209], v60 offset:32768
	ds_read_b128 v[210:213], v60 offset:40960
	s_waitcnt lgkmcnt(1)
	v_mfma_f32_16x16x32_bf16 v[134:137], v[206:209], v[162:165], v[134:137]
	v_mfma_f32_16x16x32_bf16 v[138:141], v[206:209], v[194:197], v[138:141]
	v_mfma_f32_16x16x32_bf16 v[142:145], v[206:209], v[198:201], v[142:145]
	v_mfma_f32_16x16x32_bf16 v[126:129], v[206:209], v[202:205], v[126:129]
	s_waitcnt lgkmcnt(0)
	v_mfma_f32_16x16x32_bf16 v[146:149], v[210:213], v[162:165], v[146:149]
	v_mfma_f32_16x16x32_bf16 v[150:153], v[210:213], v[194:197], v[150:153]
	v_mfma_f32_16x16x32_bf16 v[154:157], v[210:213], v[198:201], v[154:157]
	v_mfma_f32_16x16x32_bf16 v[130:133], v[210:213], v[202:205], v[130:133]
	ds_read_b128 v[206:209], v60 offset:49152
	ds_read_b128 v[210:213], v60 offset:57344
	s_waitcnt lgkmcnt(1)
	v_mfma_f32_16x16x32_bf16 v[166:169], v[206:209], v[162:165], v[166:169]
	v_mfma_f32_16x16x32_bf16 v[170:173], v[206:209], v[194:197], v[170:173]
	v_mfma_f32_16x16x32_bf16 v[174:177], v[206:209], v[198:201], v[174:177]
	v_mfma_f32_16x16x32_bf16 v[158:161], v[206:209], v[202:205], v[158:161]
	s_waitcnt lgkmcnt(0)
	v_mfma_f32_16x16x32_bf16 v[4:7], v[210:213], v[162:165], v[4:7]
	v_mfma_f32_16x16x32_bf16 v[8:11], v[210:213], v[194:197], v[8:11]
	v_mfma_f32_16x16x32_bf16 v[24:27], v[210:213], v[198:201], v[24:27]
	v_mfma_f32_16x16x32_bf16 v[32:35], v[210:213], v[202:205], v[32:35]
	v_add_co_u32_e32 v60, vcc, s68, v2
	s_nop 1
	v_addc_co_u32_e32 v61, vcc, 0, v3, vcc
	global_load_dwordx4 v[162:165], v[60:61], off
	global_load_dwordx4 v[194:197], v[60:61], off offset:1024
	global_load_dwordx4 v[198:201], v[60:61], off offset:2048
	global_load_dwordx4 v[202:205], v[60:61], off offset:3072
	v_bitop3_b32 v60, v214, v235, 20 bitop3:0x36
	v_lshlrev_b32_e32 v60, 4, v60
	v_add3_u32 v60, 0, v60, v64
	ds_read_b128 v[206:209], v60
	ds_read_b128 v[210:213], v60 offset:8192
	s_waitcnt vmcnt(7) lgkmcnt(1)
	v_mfma_f32_16x16x32_bf16 v[20:23], v[206:209], v[178:181], v[20:23]
	s_waitcnt vmcnt(6)
	v_mfma_f32_16x16x32_bf16 v[28:31], v[206:209], v[182:185], v[28:31]
	s_waitcnt vmcnt(5)
	v_mfma_f32_16x16x32_bf16 v[36:39], v[206:209], v[186:189], v[36:39]
	s_waitcnt vmcnt(4)
	v_mfma_f32_16x16x32_bf16 v[12:15], v[206:209], v[190:193], v[12:15]
	s_waitcnt lgkmcnt(0)
	v_mfma_f32_16x16x32_bf16 v[40:43], v[210:213], v[178:181], v[40:43]
	v_mfma_f32_16x16x32_bf16 v[44:47], v[210:213], v[182:185], v[44:47]
	v_mfma_f32_16x16x32_bf16 v[48:51], v[210:213], v[186:189], v[48:51]
	v_mfma_f32_16x16x32_bf16 v[16:19], v[210:213], v[190:193], v[16:19]
	ds_read_b128 v[206:209], v60 offset:16384
	ds_read_b128 v[210:213], v60 offset:24576
	s_waitcnt lgkmcnt(1)
	v_mfma_f32_16x16x32_bf16 v[72:75], v[206:209], v[178:181], v[72:75]
	v_mfma_f32_16x16x32_bf16 v[76:79], v[206:209], v[182:185], v[76:79]
	v_mfma_f32_16x16x32_bf16 v[80:83], v[206:209], v[186:189], v[80:83]
	v_mfma_f32_16x16x32_bf16 v[52:55], v[206:209], v[190:193], v[52:55]
	s_waitcnt lgkmcnt(0)
	v_mfma_f32_16x16x32_bf16 v[114:117], v[210:213], v[178:181], v[114:117]
	v_mfma_f32_16x16x32_bf16 v[118:121], v[210:213], v[182:185], v[118:121]
	v_mfma_f32_16x16x32_bf16 v[122:125], v[210:213], v[186:189], v[122:125]
	v_mfma_f32_16x16x32_bf16 v[56:59], v[210:213], v[190:193], v[56:59]
	ds_read_b128 v[206:209], v60 offset:32768
	ds_read_b128 v[210:213], v60 offset:40960
	s_waitcnt lgkmcnt(1)
	v_mfma_f32_16x16x32_bf16 v[134:137], v[206:209], v[178:181], v[134:137]
	v_mfma_f32_16x16x32_bf16 v[138:141], v[206:209], v[182:185], v[138:141]
	v_mfma_f32_16x16x32_bf16 v[142:145], v[206:209], v[186:189], v[142:145]
	v_mfma_f32_16x16x32_bf16 v[126:129], v[206:209], v[190:193], v[126:129]
	s_waitcnt lgkmcnt(0)
	v_mfma_f32_16x16x32_bf16 v[146:149], v[210:213], v[178:181], v[146:149]
	v_mfma_f32_16x16x32_bf16 v[150:153], v[210:213], v[182:185], v[150:153]
	v_mfma_f32_16x16x32_bf16 v[154:157], v[210:213], v[186:189], v[154:157]
	v_mfma_f32_16x16x32_bf16 v[130:133], v[210:213], v[190:193], v[130:133]
	ds_read_b128 v[206:209], v60 offset:49152
	ds_read_b128 v[210:213], v60 offset:57344
	s_waitcnt lgkmcnt(1)
	v_mfma_f32_16x16x32_bf16 v[166:169], v[206:209], v[178:181], v[166:169]
	v_mfma_f32_16x16x32_bf16 v[170:173], v[206:209], v[182:185], v[170:173]
	v_mfma_f32_16x16x32_bf16 v[174:177], v[206:209], v[186:189], v[174:177]
	v_mfma_f32_16x16x32_bf16 v[158:161], v[206:209], v[190:193], v[158:161]
	s_waitcnt lgkmcnt(0)
	v_mfma_f32_16x16x32_bf16 v[4:7], v[210:213], v[178:181], v[4:7]
	v_mfma_f32_16x16x32_bf16 v[8:11], v[210:213], v[182:185], v[8:11]
	v_mfma_f32_16x16x32_bf16 v[24:27], v[210:213], v[186:189], v[24:27]
	v_mfma_f32_16x16x32_bf16 v[32:35], v[210:213], v[190:193], v[32:35]
	v_add_co_u32_e32 v2, vcc, s73, v2
	s_nop 1
	v_addc_co_u32_e32 v3, vcc, 0, v3, vcc
	global_load_dwordx4 v[178:181], v[2:3], off
	global_load_dwordx4 v[182:185], v[2:3], off offset:1024
	global_load_dwordx4 v[186:189], v[2:3], off offset:2048
	global_load_dwordx4 v[190:193], v[2:3], off offset:3072
	v_bitop3_b32 v2, v214, v235, 24 bitop3:0x36
	v_lshlrev_b32_e32 v2, 4, v2
	v_add3_u32 v2, 0, v2, v64
	ds_read_b128 v[206:209], v2
	ds_read_b128 v[210:213], v2 offset:8192
	s_waitcnt vmcnt(7) lgkmcnt(1)
	v_mfma_f32_16x16x32_bf16 v[20:23], v[206:209], v[162:165], v[20:23]
	s_waitcnt vmcnt(6)
	v_mfma_f32_16x16x32_bf16 v[28:31], v[206:209], v[194:197], v[28:31]
	s_waitcnt vmcnt(5)
	v_mfma_f32_16x16x32_bf16 v[36:39], v[206:209], v[198:201], v[36:39]
	s_waitcnt vmcnt(4)
	v_mfma_f32_16x16x32_bf16 v[12:15], v[206:209], v[202:205], v[12:15]
	s_waitcnt lgkmcnt(0)
	v_mfma_f32_16x16x32_bf16 v[40:43], v[210:213], v[162:165], v[40:43]
	v_mfma_f32_16x16x32_bf16 v[44:47], v[210:213], v[194:197], v[44:47]
	v_mfma_f32_16x16x32_bf16 v[48:51], v[210:213], v[198:201], v[48:51]
	v_mfma_f32_16x16x32_bf16 v[16:19], v[210:213], v[202:205], v[16:19]
	ds_read_b128 v[206:209], v2 offset:16384
	ds_read_b128 v[210:213], v2 offset:24576
	s_waitcnt lgkmcnt(1)
	v_mfma_f32_16x16x32_bf16 v[72:75], v[206:209], v[162:165], v[72:75]
	v_mfma_f32_16x16x32_bf16 v[76:79], v[206:209], v[194:197], v[76:79]
	v_mfma_f32_16x16x32_bf16 v[80:83], v[206:209], v[198:201], v[80:83]
	v_mfma_f32_16x16x32_bf16 v[206:209], v[206:209], v[202:205], v[52:55]
	s_waitcnt lgkmcnt(0)
	v_mfma_f32_16x16x32_bf16 v[114:117], v[210:213], v[162:165], v[114:117]
	v_mfma_f32_16x16x32_bf16 v[118:121], v[210:213], v[194:197], v[118:121]
	v_mfma_f32_16x16x32_bf16 v[122:125], v[210:213], v[198:201], v[122:125]
	v_mfma_f32_16x16x32_bf16 v[210:213], v[210:213], v[202:205], v[56:59]
	ds_read_b128 v[52:55], v2 offset:32768
	s_nop 1
	ds_read_b128 v[56:59], v2 offset:40960
	s_waitcnt lgkmcnt(1)
	v_mfma_f32_16x16x32_bf16 v[134:137], v[52:55], v[162:165], v[134:137]
	v_mfma_f32_16x16x32_bf16 v[138:141], v[52:55], v[194:197], v[138:141]
	v_mfma_f32_16x16x32_bf16 v[142:145], v[52:55], v[198:201], v[142:145]
	v_mfma_f32_16x16x32_bf16 v[126:129], v[52:55], v[202:205], v[126:129]
	s_waitcnt lgkmcnt(0)
	v_mfma_f32_16x16x32_bf16 v[146:149], v[56:59], v[162:165], v[146:149]
	v_mfma_f32_16x16x32_bf16 v[150:153], v[56:59], v[194:197], v[150:153]
	v_mfma_f32_16x16x32_bf16 v[154:157], v[56:59], v[198:201], v[154:157]
	v_mfma_f32_16x16x32_bf16 v[130:133], v[56:59], v[202:205], v[130:133]
	ds_read_b128 v[52:55], v2 offset:49152
	ds_read_b128 v[56:59], v2 offset:57344
	s_waitcnt lgkmcnt(1)
	v_mfma_f32_16x16x32_bf16 v[166:169], v[52:55], v[162:165], v[166:169]
	v_mfma_f32_16x16x32_bf16 v[170:173], v[52:55], v[194:197], v[170:173]
	v_mfma_f32_16x16x32_bf16 v[174:177], v[52:55], v[198:201], v[174:177]
	v_mfma_f32_16x16x32_bf16 v[158:161], v[52:55], v[202:205], v[158:161]
	s_waitcnt lgkmcnt(0)
	v_mfma_f32_16x16x32_bf16 v[162:165], v[56:59], v[162:165], v[4:7]
	v_mfma_f32_16x16x32_bf16 v[6:9], v[56:59], v[194:197], v[8:11]
	v_mfma_f32_16x16x32_bf16 v[194:197], v[56:59], v[198:201], v[24:27]
	v_mfma_f32_16x16x32_bf16 v[198:201], v[56:59], v[202:205], v[32:35]
	v_bitop3_b32 v2, v214, v235, 28 bitop3:0x36
	v_lshlrev_b32_e32 v2, 4, v2
	v_add3_u32 v64, 0, v2, v64
	ds_read_b128 v[2:5], v64
	ds_read_b128 v[32:35], v64 offset:8192
	s_waitcnt vmcnt(3) lgkmcnt(1)
	v_mfma_f32_16x16x32_bf16 v[202:205], v[2:5], v[178:181], v[20:23]
	s_waitcnt vmcnt(2)
	v_mfma_f32_16x16x32_bf16 v[214:217], v[2:5], v[182:185], v[28:31]
	s_waitcnt vmcnt(1)
	v_mfma_f32_16x16x32_bf16 v[58:61], v[2:5], v[186:189], v[36:39]
	s_waitcnt vmcnt(0)
	v_mfma_f32_16x16x32_bf16 v[26:29], v[2:5], v[190:193], v[12:15]
	ds_read_b128 v[2:5], v64 offset:16384
	s_nop 1
	ds_read_b128 v[10:13], v64 offset:24576
	s_waitcnt lgkmcnt(2)
	v_mfma_f32_16x16x32_bf16 v[218:221], v[32:35], v[178:181], v[40:43]
	v_mfma_f32_16x16x32_bf16 v[222:225], v[32:35], v[182:185], v[44:47]
	v_mfma_f32_16x16x32_bf16 v[226:229], v[32:35], v[186:189], v[48:51]
	v_mfma_f32_16x16x32_bf16 v[30:33], v[32:35], v[190:193], v[16:19]
	s_waitcnt lgkmcnt(1)
	v_mfma_f32_16x16x32_bf16 v[230:233], v[2:5], v[178:181], v[72:75]
	v_mfma_f32_16x16x32_bf16 v[74:77], v[2:5], v[182:185], v[76:79]
	v_mfma_f32_16x16x32_bf16 v[50:53], v[2:5], v[186:189], v[80:83]
	v_mfma_f32_16x16x32_bf16 v[18:21], v[2:5], v[190:193], v[206:209]
	ds_read_b128 v[2:5], v64 offset:32768
	ds_read_b128 v[14:17], v64 offset:40960
	s_waitcnt lgkmcnt(2)
	v_mfma_f32_16x16x32_bf16 v[78:81], v[10:13], v[178:181], v[114:117]
	v_mfma_f32_16x16x32_bf16 v[114:117], v[10:13], v[182:185], v[118:121]
	v_mfma_f32_16x16x32_bf16 v[54:57], v[10:13], v[186:189], v[122:125]
	v_mfma_f32_16x16x32_bf16 v[22:25], v[10:13], v[190:193], v[210:213]
	s_waitcnt lgkmcnt(1)
	v_mfma_f32_16x16x32_bf16 v[118:121], v[2:5], v[178:181], v[134:137]
	v_mfma_f32_16x16x32_bf16 v[122:125], v[2:5], v[182:185], v[138:141]
	v_mfma_f32_16x16x32_bf16 v[42:45], v[2:5], v[186:189], v[142:145]
	v_mfma_f32_16x16x32_bf16 v[10:13], v[2:5], v[190:193], v[126:129]
	s_waitcnt lgkmcnt(0)
	v_mfma_f32_16x16x32_bf16 v[126:129], v[14:17], v[178:181], v[146:149]
	v_mfma_f32_16x16x32_bf16 v[134:137], v[14:17], v[182:185], v[150:153]
	v_mfma_f32_16x16x32_bf16 v[46:49], v[14:17], v[186:189], v[154:157]
	v_mfma_f32_16x16x32_bf16 v[14:17], v[14:17], v[190:193], v[130:133]
	ds_read_b128 v[2:5], v64 offset:49152
	s_nop 1
	ds_read_b128 v[130:133], v64 offset:57344
	s_waitcnt lgkmcnt(1)
	v_mfma_f32_16x16x32_bf16 v[138:141], v[2:5], v[178:181], v[166:169]
	v_mfma_f32_16x16x32_bf16 v[142:145], v[2:5], v[182:185], v[170:173]
	v_mfma_f32_16x16x32_bf16 v[34:37], v[2:5], v[186:189], v[174:177]
	v_mfma_f32_16x16x32_bf16 v[2:5], v[2:5], v[190:193], v[158:161]
	s_waitcnt lgkmcnt(0)
	v_mfma_f32_16x16x32_bf16 v[146:149], v[130:133], v[178:181], v[162:165]
	v_mfma_f32_16x16x32_bf16 v[150:153], v[130:133], v[182:185], v[6:9]
	v_mfma_f32_16x16x32_bf16 v[38:41], v[130:133], v[186:189], v[194:197]
	v_mfma_f32_16x16x32_bf16 v[6:9], v[130:133], v[190:193], v[198:201]
	s_ashr_i32 s45, s44, 31
	s_lshl_b64 s[46:47], s[44:45], 9
	s_add_u32 s0, s46, s59
	s_addc_u32 s45, s47, s60
	v_or_b32_e32 v72, s0, v235
	v_mov_b32_e32 v73, s45
	v_lshlrev_b64 v[72:73], 8, v[72:73]
	v_and_b32_e32 v64, 16, v234
	v_lshl_add_u64 v[72:73], s[20:21], 0, v[72:73]
	v_lshlrev_b32_e32 v64, 1, v64
	v_lshl_add_u64 v[72:73], v[72:73], 0, v[64:65]
	v_lshrrev_b32_e32 v64, 1, v234
	v_and_b32_e32 v64, 16, v64
	v_lshl_add_u64 v[72:73], v[72:73], 0, v[64:65]
	v_permlane16_swap_b32_e32 v202, v218
	v_permlane16_swap_b32_e32 v203, v219
	v_permlane16_swap_b32_e32 v204, v220
	v_permlane16_swap_b32_e32 v205, v221
	v_add_co_u32_e32 v82, vcc, s62, v72
	v_cvt_pk_bf16_f32 v130, v202, v203
	v_cvt_pk_bf16_f32 v131, v204, v205
	v_cvt_pk_bf16_f32 v132, v218, v219
	v_cvt_pk_bf16_f32 v133, v220, v221
	v_permlane16_swap_b32_e32 v230, v78
	v_permlane16_swap_b32_e32 v231, v79
	v_permlane16_swap_b32_e32 v118, v126
	v_permlane16_swap_b32_e32 v119, v127
	v_addc_co_u32_e32 v83, vcc, 0, v73, vcc
	global_store_dwordx4 v[72:73], v[130:133], off
	v_permlane16_swap_b32_e32 v232, v80
	v_permlane16_swap_b32_e32 v233, v81
	v_cvt_pk_bf16_f32 v132, v78, v79
	v_permlane16_swap_b32_e32 v120, v128
	v_permlane16_swap_b32_e32 v121, v129
	v_cvt_pk_bf16_f32 v78, v118, v119
	v_add_co_u32_e32 v118, vcc, s61, v72
	v_permlane16_swap_b32_e32 v74, v114
	v_permlane16_swap_b32_e32 v75, v115
	v_permlane16_swap_b32_e32 v76, v116
	v_permlane16_swap_b32_e32 v77, v117
	v_cvt_pk_bf16_f32 v133, v80, v81
	v_cvt_pk_bf16_f32 v79, v120, v121
	v_cvt_pk_bf16_f32 v80, v126, v127
	v_cvt_pk_bf16_f32 v81, v128, v129
	v_permlane16_swap_b32_e32 v138, v146
	v_permlane16_swap_b32_e32 v139, v147
	v_permlane16_swap_b32_e32 v140, v148
	v_permlane16_swap_b32_e32 v141, v149
	v_addc_co_u32_e32 v119, vcc, 0, v73, vcc
	v_cvt_pk_bf16_f32 v74, v74, v75
	v_cvt_pk_bf16_f32 v75, v76, v77
	v_cvt_pk_bf16_f32 v76, v114, v115
	v_cvt_pk_bf16_f32 v77, v116, v117
	v_permlane16_swap_b32_e32 v122, v134
	v_permlane16_swap_b32_e32 v123, v135
	v_permlane16_swap_b32_e32 v124, v136
	v_permlane16_swap_b32_e32 v125, v137
	v_permlane16_swap_b32_e32 v26, v30
	v_permlane16_swap_b32_e32 v27, v31
	v_permlane16_swap_b32_e32 v28, v32
	v_permlane16_swap_b32_e32 v29, v33
	global_store_dwordx4 v[72:73], v[78:81], off offset:128
	v_permlane16_swap_b32_e32 v214, v222
	s_nop 0
	v_cvt_pk_bf16_f32 v78, v138, v139
	v_cvt_pk_bf16_f32 v79, v140, v141
	v_cvt_pk_bf16_f32 v80, v146, v147
	v_cvt_pk_bf16_f32 v81, v148, v149
	v_permlane16_swap_b32_e32 v215, v223
	v_permlane16_swap_b32_e32 v216, v224
	v_permlane16_swap_b32_e32 v217, v225
	global_store_dwordx4 v[82:83], v[74:77], off offset:64
	v_permlane16_swap_b32_e32 v142, v150
	s_nop 0
	v_cvt_pk_bf16_f32 v74, v122, v123
	v_cvt_pk_bf16_f32 v75, v124, v125
	v_cvt_pk_bf16_f32 v76, v134, v135
	v_cvt_pk_bf16_f32 v77, v136, v137
	v_permlane16_swap_b32_e32 v143, v151
	v_permlane16_swap_b32_e32 v144, v152
	v_permlane16_swap_b32_e32 v145, v153
	v_permlane16_swap_b32_e32 v58, v226
	v_permlane16_swap_b32_e32 v59, v227
	v_permlane16_swap_b32_e32 v60, v228
	v_permlane16_swap_b32_e32 v61, v229
	v_permlane16_swap_b32_e32 v50, v54
	v_permlane16_swap_b32_e32 v51, v55
	v_permlane16_swap_b32_e32 v52, v56
	v_permlane16_swap_b32_e32 v53, v57
	v_permlane16_swap_b32_e32 v42, v46
	v_permlane16_swap_b32_e32 v43, v47
	v_permlane16_swap_b32_e32 v44, v48
	v_permlane16_swap_b32_e32 v45, v49
	v_permlane16_swap_b32_e32 v34, v38
	v_permlane16_swap_b32_e32 v35, v39
	v_permlane16_swap_b32_e32 v36, v40
	v_permlane16_swap_b32_e32 v37, v41
	v_cvt_pk_bf16_f32 v26, v26, v27
	v_cvt_pk_bf16_f32 v27, v28, v29
	v_cvt_pk_bf16_f32 v28, v30, v31
	v_add_co_u32_e32 v30, vcc, s63, v72
	v_permlane16_swap_b32_e32 v18, v22
	v_permlane16_swap_b32_e32 v19, v23
	v_permlane16_swap_b32_e32 v20, v24
	v_permlane16_swap_b32_e32 v21, v25
	v_permlane16_swap_b32_e32 v10, v14
	v_permlane16_swap_b32_e32 v11, v15
	v_permlane16_swap_b32_e32 v12, v16
	v_permlane16_swap_b32_e32 v13, v17
	v_permlane16_swap_b32_e32 v2, v6
	v_permlane16_swap_b32_e32 v3, v7
	v_permlane16_swap_b32_e32 v4, v8
	v_permlane16_swap_b32_e32 v5, v9
	s_add_i32 s44, s44, s52
	v_cvt_pk_bf16_f32 v130, v230, v231
	v_cvt_pk_bf16_f32 v131, v232, v233
	global_store_dwordx4 v[72:73], v[78:81], off offset:192
	global_store_dwordx4 v[82:83], v[74:77], off offset:128
	v_cvt_pk_bf16_f32 v58, v58, v59
	v_cvt_pk_bf16_f32 v78, v214, v215
	v_cvt_pk_bf16_f32 v79, v216, v217
	v_cvt_pk_bf16_f32 v80, v222, v223
	v_cvt_pk_bf16_f32 v81, v224, v225
	v_cvt_pk_bf16_f32 v74, v142, v143
	v_cvt_pk_bf16_f32 v75, v144, v145
	v_cvt_pk_bf16_f32 v76, v150, v151
	v_cvt_pk_bf16_f32 v77, v152, v153
	v_cvt_pk_bf16_f32 v59, v60, v61
	v_cvt_pk_bf16_f32 v60, v226, v227
	v_cvt_pk_bf16_f32 v61, v228, v229
	v_cvt_pk_bf16_f32 v50, v50, v51
	v_cvt_pk_bf16_f32 v51, v52, v53
	v_cvt_pk_bf16_f32 v52, v54, v55
	v_cvt_pk_bf16_f32 v53, v56, v57
	v_cvt_pk_bf16_f32 v42, v42, v43
	v_cvt_pk_bf16_f32 v43, v44, v45
	v_cvt_pk_bf16_f32 v44, v46, v47
	v_cvt_pk_bf16_f32 v45, v48, v49
	v_cvt_pk_bf16_f32 v34, v34, v35
	v_cvt_pk_bf16_f32 v35, v36, v37
	v_cvt_pk_bf16_f32 v36, v38, v39
	v_cvt_pk_bf16_f32 v37, v40, v41
	v_cvt_pk_bf16_f32 v29, v32, v33
	v_addc_co_u32_e32 v31, vcc, 0, v73, vcc
	v_cvt_pk_bf16_f32 v18, v18, v19
	v_cvt_pk_bf16_f32 v19, v20, v21
	v_cvt_pk_bf16_f32 v20, v22, v23
	v_cvt_pk_bf16_f32 v21, v24, v25
	v_cvt_pk_bf16_f32 v10, v10, v11
	v_cvt_pk_bf16_f32 v11, v12, v13
	v_cvt_pk_bf16_f32 v12, v14, v15
	v_cvt_pk_bf16_f32 v13, v16, v17
	v_cvt_pk_bf16_f32 v2, v2, v3
	v_cvt_pk_bf16_f32 v3, v4, v5
	v_cvt_pk_bf16_f32 v4, v6, v7
	v_cvt_pk_bf16_f32 v5, v8, v9
	s_cmpk_lt_i32 s44, 0x100
	global_store_dwordx4 v[72:73], v[130:133], off offset:64
	global_store_dwordx4 v[118:119], v[78:81], off offset:-4096
	global_store_dwordx4 v[82:83], v[74:77], off offset:192
	global_store_dwordx4 v[118:119], v[58:61], off
	global_store_dwordx4 v[118:119], v[50:53], off offset:64
	global_store_dwordx4 v[118:119], v[42:45], off offset:128
	global_store_dwordx4 v[118:119], v[34:37], off offset:192
	global_store_dwordx4 v[30:31], v[26:29], off
	global_store_dwordx4 v[30:31], v[18:21], off offset:64
	global_store_dwordx4 v[30:31], v[10:13], off offset:128
	global_store_dwordx4 v[30:31], v[2:5], off offset:192
	s_cbranch_scc0 .LBB0_279

.LBB0_279:
	s_setprio 0
	s_cmp_lt_i32 s79, 4
	s_cselect_b64 s[4:5], -1, 0
	s_cmp_gt_i32 s78, 4
	s_cselect_b64 s[0:1], -1, 0
	s_and_b64 s[4:5], s[4:5], s[0:1]
	s_andn2_b64 vcc, exec, s[4:5]
	s_cbranch_vccnz .LBB0_347
	s_cmp_gt_i32 s79, -1
	s_cbranch_scc0 .LBB0_294
	s_cmp_gt_u32 s58, 63
	s_mov_b64 s[6:7], 0
	s_cbranch_scc1 .LBB0_283
